# mixer queue pop-ahead in the FoX/SB epilogues on top of the widened epilogues (SB units last: the final empty pop is prefetched)
# speedup vs baseline: 1.0103x; 1.0103x over previous
.LBB0_209:
	s_or_b64 exec, exec, s[48:49]
	v_lshlrev_b32_e32 v0, 10, v129
	v_and_b32_e32 v0, 0x3000, v0
	v_add_u32_e32 v34, v120, v0
	v_ashrrev_i32_e32 v35, 31, v34
	v_lshlrev_b64 v[34:35], 11, v[34:35]
	v_lshlrev_b32_e32 v0, 7, v129
	v_lshl_add_u64 v[34:35], s[70:71], 0, v[34:35]
	v_and_b32_e32 v0, 0x180, v0
	v_lshl_add_u64 v[34:35], v[34:35], 0, v[0:1]
	v_lshlrev_b32_e32 v0, 3, v115
	v_lshl_add_u64 v[36:37], v[34:35], 0, v[0:1]
	s_mov_b64 s[38:39], 0x95c8600
	v_lshl_add_u64 v[34:35], v[36:37], 0, s[38:39]
	v_add_co_u32_e32 v36, vcc, 0x95c8000, v36
	s_nop 1
	v_addc_co_u32_e32 v37, vcc, 0, v37, vcc
	v_and_b32_e32 v96, 32, v216
	v_lshrrev_b32_e32 v96, 2, v96
	v_mov_b32_e32 v97, 0
	v_lshl_add_u64 v[98:99], v[34:35], 0, v[96:97]
	global_load_dwordx4 v[44:47], v[98:99], off
	global_load_dwordx4 v[48:51], v[98:99], off offset:32
	global_load_dwordx4 v[52:55], v[98:99], off offset:64
	global_load_dwordx4 v[56:59], v[98:99], off offset:96
	v_readfirstlane_b32 s100, v128
	s_cmp_lg_u32 s100, 0
	s_cbranch_scc1 .Lpf_skip_sb
	v_readlane_b32 s100, v250, 11
	v_readlane_b32 s101, v250, 12
	s_mov_b64 s[38:39], exec
	s_mov_b64 exec, 1
	v_mov_b32_e32 v255, 1
	s_nop 4
	global_atomic_add v255, v1, v255, s[100:101] sc0
	s_mov_b64 exec, s[38:39]
	s_mov_b32 s99, 1
.Lpf_skip_sb:
	s_mov_b32 s38, 0xbfb8aa3b
	s_mov_b32 s39, 0xbfb8aa3b
	s_mov_b32 s48, 1.0
	s_mov_b32 s49, 1.0
	s_waitcnt vmcnt(0)
	v_permlane32_swap_b32 v44, v46
	v_permlane32_swap_b32 v45, v47
	v_permlane32_swap_b32 v48, v50
	v_permlane32_swap_b32 v49, v51
	v_permlane32_swap_b32 v52, v54
	v_permlane32_swap_b32 v53, v55
	v_permlane32_swap_b32 v56, v58
	v_permlane32_swap_b32 v57, v59
	v_lshlrev_b32_e32 v64, 16, v44
	v_and_b32_e32 v65, 0xffff0000, v44
	v_lshlrev_b32_e32 v66, 16, v45
	v_and_b32_e32 v67, 0xffff0000, v45
	v_lshlrev_b32_e32 v68, 16, v46
	v_and_b32_e32 v69, 0xffff0000, v46
	v_lshlrev_b32_e32 v70, 16, v47
	v_and_b32_e32 v71, 0xffff0000, v47
	v_lshlrev_b32_e32 v72, 16, v48
	v_and_b32_e32 v73, 0xffff0000, v48
	v_lshlrev_b32_e32 v74, 16, v49
	v_and_b32_e32 v75, 0xffff0000, v49
	v_lshlrev_b32_e32 v76, 16, v50
	v_and_b32_e32 v77, 0xffff0000, v50
	v_lshlrev_b32_e32 v78, 16, v51
	v_and_b32_e32 v79, 0xffff0000, v51
	v_pk_mul_f32 v[80:81], v[64:65], s[38:39]
	v_pk_mul_f32 v[82:83], v[66:67], s[38:39]
	v_pk_mul_f32 v[84:85], v[68:69], s[38:39]
	v_pk_mul_f32 v[86:87], v[70:71], s[38:39]
	v_pk_mul_f32 v[88:89], v[72:73], s[38:39]
	v_pk_mul_f32 v[90:91], v[74:75], s[38:39]
	v_pk_mul_f32 v[92:93], v[76:77], s[38:39]
	v_pk_mul_f32 v[94:95], v[78:79], s[38:39]
	v_exp_f32_e32 v80, v80
	v_exp_f32_e32 v81, v81
	v_exp_f32_e32 v82, v82
	v_exp_f32_e32 v83, v83
	v_exp_f32_e32 v84, v84
	v_exp_f32_e32 v85, v85
	v_exp_f32_e32 v86, v86
	v_exp_f32_e32 v87, v87
	v_exp_f32_e32 v88, v88
	v_exp_f32_e32 v89, v89
	v_exp_f32_e32 v90, v90
	v_exp_f32_e32 v91, v91
	v_exp_f32_e32 v92, v92
	v_exp_f32_e32 v93, v93
	v_exp_f32_e32 v94, v94
	v_exp_f32_e32 v95, v95
	v_pk_add_f32 v[80:81], v[80:81], s[48:49]
	v_pk_add_f32 v[82:83], v[82:83], s[48:49]
	v_pk_add_f32 v[84:85], v[84:85], s[48:49]
	v_pk_add_f32 v[86:87], v[86:87], s[48:49]
	v_pk_add_f32 v[88:89], v[88:89], s[48:49]
	v_pk_add_f32 v[90:91], v[90:91], s[48:49]
	v_pk_add_f32 v[92:93], v[92:93], s[48:49]
	v_pk_add_f32 v[94:95], v[94:95], s[48:49]
	v_rcp_f32_e32 v80, v80
	v_rcp_f32_e32 v81, v81
	v_rcp_f32_e32 v82, v82
	v_rcp_f32_e32 v83, v83
	v_rcp_f32_e32 v84, v84
	v_rcp_f32_e32 v85, v85
	v_rcp_f32_e32 v86, v86
	v_rcp_f32_e32 v87, v87
	v_rcp_f32_e32 v88, v88
	v_rcp_f32_e32 v89, v89
	v_rcp_f32_e32 v90, v90
	v_rcp_f32_e32 v91, v91
	v_rcp_f32_e32 v92, v92
	v_rcp_f32_e32 v93, v93
	v_rcp_f32_e32 v94, v94
	v_rcp_f32_e32 v95, v95
	v_pk_mul_f32 v[80:81], v[80:81], v[64:65]
	v_pk_mul_f32 v[82:83], v[82:83], v[66:67]
	v_pk_mul_f32 v[84:85], v[84:85], v[68:69]
	v_pk_mul_f32 v[86:87], v[86:87], v[70:71]
	v_pk_mul_f32 v[88:89], v[88:89], v[72:73]
	v_pk_mul_f32 v[90:91], v[90:91], v[74:75]
	v_pk_mul_f32 v[92:93], v[92:93], v[76:77]
	v_pk_mul_f32 v[94:95], v[94:95], v[78:79]
	v_pk_mul_f32 v[80:81], v[2:3], v[80:81]
	v_pk_mul_f32 v[82:83], v[4:5], v[82:83]
	v_pk_mul_f32 v[84:85], v[6:7], v[84:85]
	v_pk_mul_f32 v[86:87], v[8:9], v[86:87]
	v_pk_mul_f32 v[88:89], v[10:11], v[88:89]
	v_pk_mul_f32 v[90:91], v[12:13], v[90:91]
	v_pk_mul_f32 v[92:93], v[14:15], v[92:93]
	v_pk_mul_f32 v[94:95], v[16:17], v[94:95]
	v_cvt_pk_bf16_f32 v64, v80, v81
	v_cvt_pk_bf16_f32 v65, v82, v83
	v_cvt_pk_bf16_f32 v66, v84, v85
	v_cvt_pk_bf16_f32 v67, v86, v87
	v_cvt_pk_bf16_f32 v68, v88, v89
	v_cvt_pk_bf16_f32 v69, v90, v91
	v_cvt_pk_bf16_f32 v70, v92, v93
	v_cvt_pk_bf16_f32 v71, v94, v95
	s_nop 1
	v_permlane32_swap_b32 v64, v66
	v_permlane32_swap_b32 v65, v67
	v_permlane32_swap_b32 v68, v70
	v_permlane32_swap_b32 v69, v71
	global_store_dwordx4 v[98:99], v[64:67], off
	global_store_dwordx4 v[98:99], v[68:71], off offset:32
	s_nop 1
	v_lshlrev_b32_e32 v64, 16, v52
	v_and_b32_e32 v65, 0xffff0000, v52
	v_lshlrev_b32_e32 v66, 16, v53
	v_and_b32_e32 v67, 0xffff0000, v53
	v_lshlrev_b32_e32 v68, 16, v54
	v_and_b32_e32 v69, 0xffff0000, v54
	v_lshlrev_b32_e32 v70, 16, v55
	v_and_b32_e32 v71, 0xffff0000, v55
	v_lshlrev_b32_e32 v72, 16, v56
	v_and_b32_e32 v73, 0xffff0000, v56
	v_lshlrev_b32_e32 v74, 16, v57
	v_and_b32_e32 v75, 0xffff0000, v57
	v_lshlrev_b32_e32 v76, 16, v58
	v_and_b32_e32 v77, 0xffff0000, v58
	v_lshlrev_b32_e32 v78, 16, v59
	v_and_b32_e32 v79, 0xffff0000, v59
	v_pk_mul_f32 v[80:81], v[64:65], s[38:39]
	v_pk_mul_f32 v[82:83], v[66:67], s[38:39]
	v_pk_mul_f32 v[84:85], v[68:69], s[38:39]
	v_pk_mul_f32 v[86:87], v[70:71], s[38:39]
	v_pk_mul_f32 v[88:89], v[72:73], s[38:39]
	v_pk_mul_f32 v[90:91], v[74:75], s[38:39]
	v_pk_mul_f32 v[92:93], v[76:77], s[38:39]
	v_pk_mul_f32 v[94:95], v[78:79], s[38:39]
	v_exp_f32_e32 v80, v80
	v_exp_f32_e32 v81, v81
	v_exp_f32_e32 v82, v82
	v_exp_f32_e32 v83, v83
	v_exp_f32_e32 v84, v84
	v_exp_f32_e32 v85, v85
	v_exp_f32_e32 v86, v86
	v_exp_f32_e32 v87, v87
	v_exp_f32_e32 v88, v88
	v_exp_f32_e32 v89, v89
	v_exp_f32_e32 v90, v90
	v_exp_f32_e32 v91, v91
	v_exp_f32_e32 v92, v92
	v_exp_f32_e32 v93, v93
	v_exp_f32_e32 v94, v94
	v_exp_f32_e32 v95, v95
	v_pk_add_f32 v[80:81], v[80:81], s[48:49]
	v_pk_add_f32 v[82:83], v[82:83], s[48:49]
	v_pk_add_f32 v[84:85], v[84:85], s[48:49]
	v_pk_add_f32 v[86:87], v[86:87], s[48:49]
	v_pk_add_f32 v[88:89], v[88:89], s[48:49]
	v_pk_add_f32 v[90:91], v[90:91], s[48:49]
	v_pk_add_f32 v[92:93], v[92:93], s[48:49]
	v_pk_add_f32 v[94:95], v[94:95], s[48:49]
	v_rcp_f32_e32 v80, v80
	v_rcp_f32_e32 v81, v81
	v_rcp_f32_e32 v82, v82
	v_rcp_f32_e32 v83, v83
	v_rcp_f32_e32 v84, v84
	v_rcp_f32_e32 v85, v85
	v_rcp_f32_e32 v86, v86
	v_rcp_f32_e32 v87, v87
	v_rcp_f32_e32 v88, v88
	v_rcp_f32_e32 v89, v89
	v_rcp_f32_e32 v90, v90
	v_rcp_f32_e32 v91, v91
	v_rcp_f32_e32 v92, v92
	v_rcp_f32_e32 v93, v93
	v_rcp_f32_e32 v94, v94
	v_rcp_f32_e32 v95, v95
	v_pk_mul_f32 v[80:81], v[80:81], v[64:65]
	v_pk_mul_f32 v[82:83], v[82:83], v[66:67]
	v_pk_mul_f32 v[84:85], v[84:85], v[68:69]
	v_pk_mul_f32 v[86:87], v[86:87], v[70:71]
	v_pk_mul_f32 v[88:89], v[88:89], v[72:73]
	v_pk_mul_f32 v[90:91], v[90:91], v[74:75]
	v_pk_mul_f32 v[92:93], v[92:93], v[76:77]
	v_pk_mul_f32 v[94:95], v[94:95], v[78:79]
	v_pk_mul_f32 v[80:81], v[18:19], v[80:81]
	v_pk_mul_f32 v[82:83], v[20:21], v[82:83]
	v_pk_mul_f32 v[84:85], v[22:23], v[84:85]
	v_pk_mul_f32 v[86:87], v[24:25], v[86:87]
	v_pk_mul_f32 v[88:89], v[26:27], v[88:89]
	v_pk_mul_f32 v[90:91], v[28:29], v[90:91]
	v_pk_mul_f32 v[92:93], v[30:31], v[92:93]
	v_pk_mul_f32 v[94:95], v[32:33], v[94:95]
	v_cvt_pk_bf16_f32 v64, v80, v81
	v_cvt_pk_bf16_f32 v65, v82, v83
	v_cvt_pk_bf16_f32 v66, v84, v85
	v_cvt_pk_bf16_f32 v67, v86, v87
	v_cvt_pk_bf16_f32 v68, v88, v89
	v_cvt_pk_bf16_f32 v69, v90, v91
	v_cvt_pk_bf16_f32 v70, v92, v93
	v_cvt_pk_bf16_f32 v71, v94, v95
	s_nop 1
	v_permlane32_swap_b32 v64, v66
	v_permlane32_swap_b32 v65, v67
	v_permlane32_swap_b32 v68, v70
	v_permlane32_swap_b32 v69, v71
	global_store_dwordx4 v[98:99], v[64:67], off offset:64
	global_store_dwordx4 v[98:99], v[68:71], off offset:96
	s_waitcnt lgkmcnt(0)
	s_barrier

.LBB0_257:
	s_or_b64 exec, exec, s[42:43]
	v_xor_b32_e32 v0, 32, v216
	v_add_u32_e32 v2, 64, v113
	v_cmp_lt_i32_e32 vcc, v0, v2
	v_readlane_b32 s38, v251, 27
	v_readlane_b32 s39, v251, 28
	v_cndmask_b32_e32 v0, v216, v0, vcc
	v_lshlrev_b32_e32 v0, 2, v0
	ds_bpermute_b32 v0, v0, v148
	s_waitcnt lgkmcnt(0)
	v_add_f32_e32 v0, v148, v0
	v_rcp_f32_e32 v4, v0
	v_lshlrev_b32_e32 v0, 9, v120
	v_and_b32_e32 v0, 0x3000, v0
	v_add_u32_e32 v2, v112, v0
	v_ashrrev_i32_e32 v3, 31, v2
	v_lshlrev_b64 v[2:3], 11, v[2:3]
	v_lshlrev_b32_e32 v0, 7, v120
	v_lshl_add_u64 v[2:3], s[38:39], 0, v[2:3]
	v_and_b32_e32 v0, 0x380, v0
	v_lshl_add_u64 v[2:3], v[2:3], 0, v[0:1]
	v_lshlrev_b32_e32 v0, 3, v121
	v_lshl_add_u64 v[2:3], v[2:3], 0, v[0:1]
	v_and_b32_e32 v96, 32, v216
	v_lshrrev_b32_e32 v96, 2, v96
	v_mov_b32_e32 v97, 0
	v_lshl_add_u64 v[98:99], v[2:3], 0, v[96:97]
	global_load_dwordx4 v[192:195], v[98:99], off
	global_load_dwordx4 v[196:199], v[98:99], off offset:32
	global_load_dwordx4 v[200:203], v[98:99], off offset:64
	global_load_dwordx4 v[204:207], v[98:99], off offset:96
	v_readfirstlane_b32 s100, v128
	s_cmp_lg_u32 s100, 0
	s_cbranch_scc1 .Lpf_skip_fox
	v_readlane_b32 s100, v250, 11
	v_readlane_b32 s101, v250, 12
	s_mov_b64 s[44:45], exec
	s_mov_b64 exec, 1
	v_mov_b32_e32 v255, 1
	s_nop 4
	global_atomic_add v255, v1, v255, s[100:101] sc0
	s_mov_b64 exec, s[44:45]
	s_mov_b32 s99, 1
.Lpf_skip_fox:
	s_mov_b32 s44, 0xbfb8aa3b
	s_mov_b32 s45, 0xbfb8aa3b
	s_mov_b32 s46, 1.0
	s_mov_b32 s47, 1.0
	v_pk_mul_f32 v[32:33], v[32:33], v[4:5] op_sel_hi:[1,0]
	v_pk_mul_f32 v[34:35], v[34:35], v[4:5] op_sel_hi:[1,0]
	v_pk_mul_f32 v[36:37], v[36:37], v[4:5] op_sel_hi:[1,0]
	v_pk_mul_f32 v[38:39], v[38:39], v[4:5] op_sel_hi:[1,0]
	v_pk_mul_f32 v[40:41], v[40:41], v[4:5] op_sel_hi:[1,0]
	v_pk_mul_f32 v[42:43], v[42:43], v[4:5] op_sel_hi:[1,0]
	v_pk_mul_f32 v[44:45], v[44:45], v[4:5] op_sel_hi:[1,0]
	v_pk_mul_f32 v[46:47], v[46:47], v[4:5] op_sel_hi:[1,0]
	v_pk_mul_f32 v[16:17], v[16:17], v[4:5] op_sel_hi:[1,0]
	v_pk_mul_f32 v[18:19], v[18:19], v[4:5] op_sel_hi:[1,0]
	v_pk_mul_f32 v[20:21], v[20:21], v[4:5] op_sel_hi:[1,0]
	v_pk_mul_f32 v[22:23], v[22:23], v[4:5] op_sel_hi:[1,0]
	v_pk_mul_f32 v[24:25], v[24:25], v[4:5] op_sel_hi:[1,0]
	v_pk_mul_f32 v[26:27], v[26:27], v[4:5] op_sel_hi:[1,0]
	v_pk_mul_f32 v[28:29], v[28:29], v[4:5] op_sel_hi:[1,0]
	v_pk_mul_f32 v[30:31], v[30:31], v[4:5] op_sel_hi:[1,0]
	s_waitcnt vmcnt(0)
	v_permlane32_swap_b32 v192, v194
	v_permlane32_swap_b32 v193, v195
	v_permlane32_swap_b32 v196, v198
	v_permlane32_swap_b32 v197, v199
	v_permlane32_swap_b32 v200, v202
	v_permlane32_swap_b32 v201, v203
	v_permlane32_swap_b32 v204, v206
	v_permlane32_swap_b32 v205, v207
	v_lshlrev_b32_e32 v64, 16, v192
	v_and_b32_e32 v65, 0xffff0000, v192
	v_lshlrev_b32_e32 v66, 16, v193
	v_and_b32_e32 v67, 0xffff0000, v193
	v_lshlrev_b32_e32 v68, 16, v194
	v_and_b32_e32 v69, 0xffff0000, v194
	v_lshlrev_b32_e32 v70, 16, v195
	v_and_b32_e32 v71, 0xffff0000, v195
	v_lshlrev_b32_e32 v72, 16, v196
	v_and_b32_e32 v73, 0xffff0000, v196
	v_lshlrev_b32_e32 v74, 16, v197
	v_and_b32_e32 v75, 0xffff0000, v197
	v_lshlrev_b32_e32 v76, 16, v198
	v_and_b32_e32 v77, 0xffff0000, v198
	v_lshlrev_b32_e32 v78, 16, v199
	v_and_b32_e32 v79, 0xffff0000, v199
	v_pk_mul_f32 v[80:81], v[64:65], s[44:45]
	v_pk_mul_f32 v[82:83], v[66:67], s[44:45]
	v_pk_mul_f32 v[84:85], v[68:69], s[44:45]
	v_pk_mul_f32 v[86:87], v[70:71], s[44:45]
	v_pk_mul_f32 v[88:89], v[72:73], s[44:45]
	v_pk_mul_f32 v[90:91], v[74:75], s[44:45]
	v_pk_mul_f32 v[92:93], v[76:77], s[44:45]
	v_pk_mul_f32 v[94:95], v[78:79], s[44:45]
	v_exp_f32_e32 v80, v80
	v_exp_f32_e32 v81, v81
	v_exp_f32_e32 v82, v82
	v_exp_f32_e32 v83, v83
	v_exp_f32_e32 v84, v84
	v_exp_f32_e32 v85, v85
	v_exp_f32_e32 v86, v86
	v_exp_f32_e32 v87, v87
	v_exp_f32_e32 v88, v88
	v_exp_f32_e32 v89, v89
	v_exp_f32_e32 v90, v90
	v_exp_f32_e32 v91, v91
	v_exp_f32_e32 v92, v92
	v_exp_f32_e32 v93, v93
	v_exp_f32_e32 v94, v94
	v_exp_f32_e32 v95, v95
	v_pk_add_f32 v[80:81], v[80:81], s[46:47]
	v_pk_add_f32 v[82:83], v[82:83], s[46:47]
	v_pk_add_f32 v[84:85], v[84:85], s[46:47]
	v_pk_add_f32 v[86:87], v[86:87], s[46:47]
	v_pk_add_f32 v[88:89], v[88:89], s[46:47]
	v_pk_add_f32 v[90:91], v[90:91], s[46:47]
	v_pk_add_f32 v[92:93], v[92:93], s[46:47]
	v_pk_add_f32 v[94:95], v[94:95], s[46:47]
	v_rcp_f32_e32 v80, v80
	v_rcp_f32_e32 v81, v81
	v_rcp_f32_e32 v82, v82
	v_rcp_f32_e32 v83, v83
	v_rcp_f32_e32 v84, v84
	v_rcp_f32_e32 v85, v85
	v_rcp_f32_e32 v86, v86
	v_rcp_f32_e32 v87, v87
	v_rcp_f32_e32 v88, v88
	v_rcp_f32_e32 v89, v89
	v_rcp_f32_e32 v90, v90
	v_rcp_f32_e32 v91, v91
	v_rcp_f32_e32 v92, v92
	v_rcp_f32_e32 v93, v93
	v_rcp_f32_e32 v94, v94
	v_rcp_f32_e32 v95, v95
	v_pk_mul_f32 v[80:81], v[80:81], v[64:65]
	v_pk_mul_f32 v[82:83], v[82:83], v[66:67]
	v_pk_mul_f32 v[84:85], v[84:85], v[68:69]
	v_pk_mul_f32 v[86:87], v[86:87], v[70:71]
	v_pk_mul_f32 v[88:89], v[88:89], v[72:73]
	v_pk_mul_f32 v[90:91], v[90:91], v[74:75]
	v_pk_mul_f32 v[92:93], v[92:93], v[76:77]
	v_pk_mul_f32 v[94:95], v[94:95], v[78:79]
	v_pk_mul_f32 v[80:81], v[32:33], v[80:81]
	v_pk_mul_f32 v[82:83], v[34:35], v[82:83]
	v_pk_mul_f32 v[84:85], v[36:37], v[84:85]
	v_pk_mul_f32 v[86:87], v[38:39], v[86:87]
	v_pk_mul_f32 v[88:89], v[40:41], v[88:89]
	v_pk_mul_f32 v[90:91], v[42:43], v[90:91]
	v_pk_mul_f32 v[92:93], v[44:45], v[92:93]
	v_pk_mul_f32 v[94:95], v[46:47], v[94:95]
	v_cvt_pk_bf16_f32 v64, v80, v81
	v_cvt_pk_bf16_f32 v65, v82, v83
	v_cvt_pk_bf16_f32 v66, v84, v85
	v_cvt_pk_bf16_f32 v67, v86, v87
	v_cvt_pk_bf16_f32 v68, v88, v89
	v_cvt_pk_bf16_f32 v69, v90, v91
	v_cvt_pk_bf16_f32 v70, v92, v93
	v_cvt_pk_bf16_f32 v71, v94, v95
	s_nop 1
	v_permlane32_swap_b32 v64, v66
	v_permlane32_swap_b32 v65, v67
	v_permlane32_swap_b32 v68, v70
	v_permlane32_swap_b32 v69, v71
	global_store_dwordx4 v[98:99], v[64:67], off
	global_store_dwordx4 v[98:99], v[68:71], off offset:32
	s_nop 1
	v_lshlrev_b32_e32 v64, 16, v200
	v_and_b32_e32 v65, 0xffff0000, v200
	v_lshlrev_b32_e32 v66, 16, v201
	v_and_b32_e32 v67, 0xffff0000, v201
	v_lshlrev_b32_e32 v68, 16, v202
	v_and_b32_e32 v69, 0xffff0000, v202
	v_lshlrev_b32_e32 v70, 16, v203
	v_and_b32_e32 v71, 0xffff0000, v203
	v_lshlrev_b32_e32 v72, 16, v204
	v_and_b32_e32 v73, 0xffff0000, v204
	v_lshlrev_b32_e32 v74, 16, v205
	v_and_b32_e32 v75, 0xffff0000, v205
	v_lshlrev_b32_e32 v76, 16, v206
	v_and_b32_e32 v77, 0xffff0000, v206
	v_lshlrev_b32_e32 v78, 16, v207
	v_and_b32_e32 v79, 0xffff0000, v207
	v_pk_mul_f32 v[80:81], v[64:65], s[44:45]
	v_pk_mul_f32 v[82:83], v[66:67], s[44:45]
	v_pk_mul_f32 v[84:85], v[68:69], s[44:45]
	v_pk_mul_f32 v[86:87], v[70:71], s[44:45]
	v_pk_mul_f32 v[88:89], v[72:73], s[44:45]
	v_pk_mul_f32 v[90:91], v[74:75], s[44:45]
	v_pk_mul_f32 v[92:93], v[76:77], s[44:45]
	v_pk_mul_f32 v[94:95], v[78:79], s[44:45]
	v_exp_f32_e32 v80, v80
	v_exp_f32_e32 v81, v81
	v_exp_f32_e32 v82, v82
	v_exp_f32_e32 v83, v83
	v_exp_f32_e32 v84, v84
	v_exp_f32_e32 v85, v85
	v_exp_f32_e32 v86, v86
	v_exp_f32_e32 v87, v87
	v_exp_f32_e32 v88, v88
	v_exp_f32_e32 v89, v89
	v_exp_f32_e32 v90, v90
	v_exp_f32_e32 v91, v91
	v_exp_f32_e32 v92, v92
	v_exp_f32_e32 v93, v93
	v_exp_f32_e32 v94, v94
	v_exp_f32_e32 v95, v95
	v_pk_add_f32 v[80:81], v[80:81], s[46:47]
	v_pk_add_f32 v[82:83], v[82:83], s[46:47]
	v_pk_add_f32 v[84:85], v[84:85], s[46:47]
	v_pk_add_f32 v[86:87], v[86:87], s[46:47]
	v_pk_add_f32 v[88:89], v[88:89], s[46:47]
	v_pk_add_f32 v[90:91], v[90:91], s[46:47]
	v_pk_add_f32 v[92:93], v[92:93], s[46:47]
	v_pk_add_f32 v[94:95], v[94:95], s[46:47]
	v_rcp_f32_e32 v80, v80
	v_rcp_f32_e32 v81, v81
	v_rcp_f32_e32 v82, v82
	v_rcp_f32_e32 v83, v83
	v_rcp_f32_e32 v84, v84
	v_rcp_f32_e32 v85, v85
	v_rcp_f32_e32 v86, v86
	v_rcp_f32_e32 v87, v87
	v_rcp_f32_e32 v88, v88
	v_rcp_f32_e32 v89, v89
	v_rcp_f32_e32 v90, v90
	v_rcp_f32_e32 v91, v91
	v_rcp_f32_e32 v92, v92
	v_rcp_f32_e32 v93, v93
	v_rcp_f32_e32 v94, v94
	v_rcp_f32_e32 v95, v95
	v_pk_mul_f32 v[80:81], v[80:81], v[64:65]
	v_pk_mul_f32 v[82:83], v[82:83], v[66:67]
	v_pk_mul_f32 v[84:85], v[84:85], v[68:69]
	v_pk_mul_f32 v[86:87], v[86:87], v[70:71]
	v_pk_mul_f32 v[88:89], v[88:89], v[72:73]
	v_pk_mul_f32 v[90:91], v[90:91], v[74:75]
	v_pk_mul_f32 v[92:93], v[92:93], v[76:77]
	v_pk_mul_f32 v[94:95], v[94:95], v[78:79]
	v_pk_mul_f32 v[80:81], v[16:17], v[80:81]
	v_pk_mul_f32 v[82:83], v[18:19], v[82:83]
	v_pk_mul_f32 v[84:85], v[20:21], v[84:85]
	v_pk_mul_f32 v[86:87], v[22:23], v[86:87]
	v_pk_mul_f32 v[88:89], v[24:25], v[88:89]
	v_pk_mul_f32 v[90:91], v[26:27], v[90:91]
	v_pk_mul_f32 v[92:93], v[28:29], v[92:93]
	v_pk_mul_f32 v[94:95], v[30:31], v[94:95]
	v_cvt_pk_bf16_f32 v64, v80, v81
	v_cvt_pk_bf16_f32 v65, v82, v83
	v_cvt_pk_bf16_f32 v66, v84, v85
	v_cvt_pk_bf16_f32 v67, v86, v87
	v_cvt_pk_bf16_f32 v68, v88, v89
	v_cvt_pk_bf16_f32 v69, v90, v91
	v_cvt_pk_bf16_f32 v70, v92, v93
	v_cvt_pk_bf16_f32 v71, v94, v95
	s_nop 1
	v_permlane32_swap_b32 v64, v66
	v_permlane32_swap_b32 v65, v67
	v_permlane32_swap_b32 v68, v70
	v_permlane32_swap_b32 v69, v71
	global_store_dwordx4 v[98:99], v[64:67], off offset:64
	global_store_dwordx4 v[98:99], v[68:71], off offset:96
